# phase_p0b row-norm loop: g and scale quads loaded once per iteration instead of per 256-column group behind full waits
# baseline (speedup 1.0000x reference)
.LBB0_98:
	s_or_b64 exec, exec, s[16:17]
	s_nop 0
	s_nop 0
	v_lshl_add_u64 v[34:35], v[34:35], 0, s[6:7]
	v_cmp_lt_i32_e32 vcc, s20, v34
	v_lshl_add_u64 v[40:41], v[40:41], 0, s[8:9]
	s_or_b64 s[12:13], vcc, s[12:13]
	v_lshl_add_u64 v[42:43], v[42:43], 0, s[10:11]
	v_pk_add_f32 v[18:19], v[102:103], 1.0 op_sel_hi:[1,0]
	v_pk_add_f32 v[16:17], v[100:101], 1.0 op_sel_hi:[1,0]
	v_pk_mul_f32 v[18:19], v[118:119], v[18:19]
	v_pk_mul_f32 v[16:17], v[116:117], v[16:17]
	v_pk_mul_f32 v[14:15], v[14:15], v[18:19]
	v_pk_mul_f32 v[12:13], v[12:13], v[16:17]
	s_nop 0
	v_cvt_pk_bf16_f32 v12, v12, v13
	v_cvt_pk_bf16_f32 v13, v14, v15
	global_store_dwordx2 v[50:51], v[12:13], off offset:2048
	s_nop 0
	s_nop 0
	s_nop 0
	v_pk_add_f32 v[14:15], v[106:107], 1.0 op_sel_hi:[1,0]
	v_pk_add_f32 v[12:13], v[104:105], 1.0 op_sel_hi:[1,0]
	v_pk_mul_f32 v[14:15], v[122:123], v[14:15]
	v_pk_mul_f32 v[12:13], v[120:121], v[12:13]
	v_pk_mul_f32 v[10:11], v[10:11], v[14:15]
	v_pk_mul_f32 v[8:9], v[8:9], v[12:13]
	s_nop 0
	v_cvt_pk_bf16_f32 v8, v8, v9
	v_cvt_pk_bf16_f32 v9, v10, v11
	global_store_dwordx2 v[50:51], v[8:9], off offset:2560
	s_nop 0
	s_nop 0
	s_nop 0
	v_pk_add_f32 v[10:11], v[110:111], 1.0 op_sel_hi:[1,0]
	v_pk_add_f32 v[8:9], v[108:109], 1.0 op_sel_hi:[1,0]
	v_pk_mul_f32 v[10:11], v[126:127], v[10:11]
	v_pk_mul_f32 v[8:9], v[124:125], v[8:9]
	v_pk_mul_f32 v[6:7], v[6:7], v[10:11]
	v_pk_mul_f32 v[4:5], v[4:5], v[8:9]
	s_nop 0
	v_cvt_pk_bf16_f32 v4, v4, v5
	v_cvt_pk_bf16_f32 v5, v6, v7
	global_store_dwordx2 v[50:51], v[4:5], off offset:3072
	s_nop 0
	s_nop 0
	s_nop 0
	v_pk_add_f32 v[6:7], v[114:115], 1.0 op_sel_hi:[1,0]
	v_pk_add_f32 v[4:5], v[112:113], 1.0 op_sel_hi:[1,0]
	v_pk_mul_f32 v[6:7], v[130:131], v[6:7]
	v_pk_mul_f32 v[4:5], v[128:129], v[4:5]
	v_pk_mul_f32 v[2:3], v[2:3], v[6:7]
	v_pk_mul_f32 v[0:1], v[0:1], v[4:5]
	s_nop 0
	v_cvt_pk_bf16_f32 v0, v0, v1
	v_cvt_pk_bf16_f32 v1, v2, v3
	global_store_dwordx2 v[50:51], v[0:1], off offset:3584
	s_andn2_b64 exec, exec, s[12:13]
	s_cbranch_execz .LBB0_103
.LBB0_99:
	v_add_u32_e32 v0, 0xffffc000, v34
	v_cmp_gt_i32_e32 vcc, s18, v34
	s_nop 1
	v_cndmask_b32_e32 v1, 0, v35, vcc
	v_cndmask_b32_e32 v0, v0, v34, vcc
	v_cndmask_b32_e32 v3, v67, v68, vcc
	v_cndmask_b32_e32 v2, v69, v70, vcc
	v_lshlrev_b64 v[0:1], 12, v[0:1]
	v_lshl_add_u64 v[0:1], v[2:3], 0, v[0:1]
	v_lshl_add_u64 v[0:1], v[0:1], 0, v[36:37]
	global_load_dwordx4 v[28:31], v[0:1], off
	global_load_dwordx4 v[24:27], v[0:1], off offset:1024
	global_load_dwordx4 v[20:23], v[0:1], off offset:2048
	global_load_dwordx4 v[16:19], v[0:1], off offset:3072
	v_lshl_add_u64 v[0:1], v[34:35], 0, 1
	v_add_u32_e32 v2, 0xffffc001, v34
	v_cmp_gt_i32_e32 vcc, s18, v0
	s_waitcnt vmcnt(3)
	v_mul_f32_e32 v45, v29, v29
	v_cndmask_b32_e32 v1, 0, v1, vcc
	v_cndmask_b32_e32 v0, v2, v0, vcc
	v_cndmask_b32_e32 v3, v67, v68, vcc
	v_cndmask_b32_e32 v2, v69, v70, vcc
	v_lshlrev_b64 v[0:1], 12, v[0:1]
	v_lshl_add_u64 v[0:1], v[2:3], 0, v[0:1]
	v_lshl_add_u64 v[50:51], v[0:1], 0, v[36:37]
	global_load_dwordx4 v[12:15], v[50:51], off
	global_load_dwordx4 v[8:11], v[50:51], off offset:1024
	global_load_dwordx4 v[4:7], v[50:51], off offset:2048
	global_load_dwordx4 v[0:3], v[50:51], off offset:3072
	v_min_i32_e32 v96, 0x4000, v34
	v_ashrrev_i32_e32 v96, 12, v96
	v_mul_hi_i32_i24_e32 v99, 0x9000, v96
	v_mul_i32_i24_e32 v98, 0x9000, v96
	v_lshl_add_u64 v[98:99], s[2:3], 0, v[98:99]
	v_lshl_add_u64 v[98:99], v[98:99], 0, s[14:15]
	v_lshl_add_u64 v[98:99], v[98:99], 0, v[36:37]
	global_load_dwordx4 v[100:103], v[98:99], off
	global_load_dwordx4 v[104:107], v[98:99], off offset:1024
	global_load_dwordx4 v[108:111], v[98:99], off offset:2048
	global_load_dwordx4 v[112:115], v[98:99], off offset:3072
	global_load_dwordx4 v[116:119], v[38:39], off
	global_load_dwordx4 v[120:123], v[38:39], off offset:1024
	global_load_dwordx4 v[124:127], v[38:39], off offset:2048
	global_load_dwordx4 v[128:131], v[38:39], off offset:3072
	v_mul_f32_e32 v47, v31, v31
	s_waitcnt vmcnt(14)
	v_mul_f32_e32 v49, v25, v25
	v_mul_f32_e32 v50, v27, v27
	s_waitcnt vmcnt(13)
	v_mul_f32_e32 v51, v21, v21
	v_mul_f32_e32 v52, v23, v23
	v_fmac_f32_e32 v45, v28, v28
	v_fmac_f32_e32 v47, v30, v30
	v_fmac_f32_e32 v49, v24, v24
	v_fmac_f32_e32 v50, v26, v26
	v_fmac_f32_e32 v51, v20, v20
	v_fmac_f32_e32 v52, v22, v22
	v_add_f32_e32 v45, v45, v47
	v_add_f32_e32 v47, v49, v50
	s_waitcnt vmcnt(12)
	v_mul_f32_e32 v53, v17, v17
	v_mul_f32_e32 v54, v19, v19
	v_add_f32_e32 v49, v51, v52
	v_add_f32_e32 v45, v45, v47
	v_fmac_f32_e32 v53, v16, v16
	v_fmac_f32_e32 v54, v18, v18
	v_add_f32_e32 v50, v53, v54
	v_add_f32_e32 v45, v45, v49
	v_add_f32_e32 v45, v45, v50
	ds_bpermute_b32 v49, v61, v45
	s_waitcnt lgkmcnt(0)
	v_add_f32_e32 v45, v45, v49
	ds_bpermute_b32 v49, v62, v45
	s_waitcnt lgkmcnt(0)
	v_add_f32_e32 v45, v45, v49
	ds_bpermute_b32 v49, v63, v45
	s_waitcnt lgkmcnt(0)
	v_add_f32_e32 v45, v45, v49
	ds_bpermute_b32 v49, v64, v45
	s_waitcnt lgkmcnt(0)
	v_add_f32_e32 v45, v45, v49
	ds_bpermute_b32 v49, v65, v45
	s_waitcnt lgkmcnt(0)
	v_add_f32_e32 v45, v45, v49
	s_waitcnt vmcnt(11)
	v_mul_f32_e32 v55, v13, v13
	v_mul_f32_e32 v56, v15, v15
	s_waitcnt vmcnt(10)
	v_mul_f32_e32 v57, v9, v9
	v_mul_f32_e32 v71, v11, v11
	s_waitcnt vmcnt(9)
	v_mul_f32_e32 v72, v5, v5
	v_mul_f32_e32 v73, v7, v7
	v_fmac_f32_e32 v55, v12, v12
	v_fmac_f32_e32 v56, v14, v14
	v_fmac_f32_e32 v57, v8, v8
	v_fmac_f32_e32 v71, v10, v10
	s_waitcnt vmcnt(8)
	v_mul_f32_e32 v74, v1, v1
	v_mul_f32_e32 v75, v3, v3
	v_fmac_f32_e32 v72, v4, v4
	v_fmac_f32_e32 v73, v6, v6
	v_add_f32_e32 v47, v55, v56
	v_add_f32_e32 v51, v57, v71
	v_fmac_f32_e32 v74, v0, v0
	v_fmac_f32_e32 v75, v2, v2
	v_add_f32_e32 v52, v72, v73
	v_add_f32_e32 v47, v47, v51
	v_add_f32_e32 v53, v74, v75
	v_add_f32_e32 v47, v47, v52
	v_add_f32_e32 v47, v47, v53
	ds_bpermute_b32 v50, v61, v47
	v_lshl_add_u64 v[52:53], s[2:3], 0, v[42:43]
	s_waitcnt lgkmcnt(0)
	v_add_f32_e32 v47, v47, v50
	ds_bpermute_b32 v50, v62, v47
	s_waitcnt lgkmcnt(0)
	v_add_f32_e32 v47, v47, v50
	ds_bpermute_b32 v50, v63, v47
	s_waitcnt lgkmcnt(0)
	v_add_f32_e32 v47, v47, v50
	ds_bpermute_b32 v50, v64, v47
	s_waitcnt lgkmcnt(0)
	v_add_f32_e32 v50, v47, v50
	ds_bpermute_b32 v51, v65, v50
	ds_bpermute_b32 v47, v66, v45
	s_waitcnt lgkmcnt(1)
	v_add_f32_e32 v71, v50, v51
	ds_bpermute_b32 v72, v66, v71
	s_waitcnt vmcnt(0)
	s_and_saveexec_b64 s[16:17], s[0:1]
	s_cbranch_execz .LBB0_101
	v_add_co_u32_e32 v50, vcc, 0x180000, v52
	s_waitcnt lgkmcnt(1)
	v_add_f32_e32 v45, v45, v47
	v_addc_co_u32_e32 v51, vcc, 0, v53, vcc
	global_store_dword v[50:51], v45, off
.LBB0_101:
	s_or_b64 exec, exec, s[16:17]
	v_min_i32_e32 v45, 0x4000, v34
	v_ashrrev_i32_e32 v45, 12, v45
	v_mul_hi_i32_i24_e32 v51, 0x9000, v45
	v_mul_i32_i24_e32 v50, 0x9000, v45
	v_lshl_add_u64 v[50:51], s[2:3], 0, v[50:51]
	v_lshl_add_u64 v[82:83], v[50:51], 0, s[14:15]
	v_lshl_add_u64 v[54:55], v[82:83], 0, v[36:37]
	s_nop 0
	s_nop 0
	v_lshl_add_u64 v[50:51], s[2:3], 0, v[40:41]
	v_add_co_u32_e32 v50, vcc, s19, v50
	v_mov_b32_e32 v45, v37
	s_nop 0
	v_addc_co_u32_e32 v51, vcc, 0, v51, vcc
	v_lshl_add_u64 v[56:57], v[82:83], 0, v[44:45]
	s_waitcnt lgkmcnt(1)
	v_mov_b32_e32 v47, v37
	v_mov_b32_e32 v49, v37
	v_pk_add_f32 v[76:77], v[102:103], 1.0 op_sel_hi:[1,0]
	v_pk_add_f32 v[74:75], v[100:101], 1.0 op_sel_hi:[1,0]
	v_pk_mul_f32 v[76:77], v[118:119], v[76:77]
	v_pk_mul_f32 v[74:75], v[116:117], v[74:75]
	v_pk_mul_f32 v[30:31], v[30:31], v[76:77]
	v_pk_mul_f32 v[28:29], v[28:29], v[74:75]
	s_nop 0
	v_cvt_pk_bf16_f32 v28, v28, v29
	v_cvt_pk_bf16_f32 v29, v30, v31
	global_store_dwordx2 v[50:51], v[28:29], off
	s_nop 0
	s_nop 0
	v_lshl_add_u64 v[28:29], v[82:83], 0, v[46:47]
	v_pk_add_f32 v[30:31], v[106:107], 1.0 op_sel_hi:[1,0]
	v_pk_add_f32 v[74:75], v[104:105], 1.0 op_sel_hi:[1,0]
	v_pk_mul_f32 v[30:31], v[122:123], v[30:31]
	v_pk_mul_f32 v[74:75], v[120:121], v[74:75]
	v_pk_mul_f32 v[26:27], v[26:27], v[30:31]
	v_pk_mul_f32 v[24:25], v[24:25], v[74:75]
	s_nop 0
	v_cvt_pk_bf16_f32 v24, v24, v25
	v_cvt_pk_bf16_f32 v25, v26, v27
	global_store_dwordx2 v[50:51], v[24:25], off offset:512
	s_nop 0
	s_nop 0
	v_lshl_add_u64 v[24:25], v[82:83], 0, v[48:49]
	v_pk_add_f32 v[26:27], v[110:111], 1.0 op_sel_hi:[1,0]
	v_pk_add_f32 v[30:31], v[108:109], 1.0 op_sel_hi:[1,0]
	v_pk_mul_f32 v[26:27], v[126:127], v[26:27]
	v_pk_mul_f32 v[30:31], v[124:125], v[30:31]
	v_pk_mul_f32 v[22:23], v[22:23], v[26:27]
	v_pk_mul_f32 v[20:21], v[20:21], v[30:31]
	s_nop 0
	v_cvt_pk_bf16_f32 v20, v20, v21
	v_cvt_pk_bf16_f32 v21, v22, v23
	global_store_dwordx2 v[50:51], v[20:21], off offset:1024
	s_nop 0
	s_nop 0
	s_nop 0
	v_pk_add_f32 v[22:23], v[114:115], 1.0 op_sel_hi:[1,0]
	v_pk_add_f32 v[20:21], v[112:113], 1.0 op_sel_hi:[1,0]
	v_pk_mul_f32 v[22:23], v[130:131], v[22:23]
	v_pk_mul_f32 v[20:21], v[128:129], v[20:21]
	v_pk_mul_f32 v[18:19], v[18:19], v[22:23]
	v_pk_mul_f32 v[16:17], v[16:17], v[20:21]
	s_nop 0
	v_cvt_pk_bf16_f32 v16, v16, v17
	v_cvt_pk_bf16_f32 v17, v18, v19
	global_store_dwordx2 v[50:51], v[16:17], off offset:1536
	s_and_saveexec_b64 s[16:17], s[0:1]
	s_cbranch_execz .LBB0_98
	v_add_co_u32_e32 v16, vcc, 0x180000, v52
	s_waitcnt lgkmcnt(0)
	v_add_f32_e32 v18, v71, v72
	v_addc_co_u32_e32 v17, vcc, 0, v53, vcc
	global_store_dword v[16:17], v18, off offset:4
	s_branch .LBB0_98
